# adds: redundant post-barrier lgkmcnt(0) removed from the three GEMM K-loops (12 sites)
# speedup vs baseline: 1.0187x; 1.0187x over previous
.LBB0_183:
	ds_read_b128 v[134:137], v157
	ds_read_b128 v[138:141], v157 offset:1024
	ds_read_b128 v[142:145], v157 offset:2048
	ds_read_b128 v[146:149], v157 offset:3072
	ds_read_b128 v[162:165], v158
	ds_read_b128 v[166:169], v158 offset:1024
	ds_read_b128 v[170:173], v158 offset:2048
	ds_read_b128 v[174:177], v158 offset:3072
	s_add_u32 s8, s6, 0xfff80080
	s_addc_u32 s9, s7, -1
	s_cmp_eq_u32 s87, 28
	s_cselect_b32 s9, s5, s9
	s_cselect_b32 s8, s39, s8
	s_cselect_b32 s11, s46, s53
	s_cselect_b32 s10, s47, s52
	v_mov_b32_e32 v128, v223
	ds_read_b128 v[178:181], v159
	ds_read_b128 v[182:185], v159 offset:1024
	ds_read_b128 v[186:189], v159 offset:2048
	ds_read_b128 v[190:193], v159 offset:3072
	ds_read_b128 v[194:197], v159 offset:4096
	ds_read_b128 v[198:201], v159 offset:5120
	ds_read_b128 v[210:213], v159 offset:6144
	ds_read_b128 v[214:217], v159 offset:7168
	s_add_i32 m0, s3, 0xc000
	s_nop 0
	global_load_lds_dwordx4 v128, s[6:7]
	v_mov_b32_e32 v128, v154
	s_add_i32 m0, s3, 0xe000
	s_nop 0
	global_load_lds_dwordx4 v128, s[6:7]
	s_waitcnt vmcnt(8)
	s_waitcnt lgkmcnt(0)
	s_barrier
	s_setprio 1
	v_mfma_scale_f32_16x16x128_f8f6f4 v[124:127], v[134:141], v[178:185], v[124:127], v160, v160 op_sel_hi:[0,0,0]
	v_mfma_scale_f32_16x16x128_f8f6f4 v[120:123], v[142:149], v[178:185], v[120:123], v160, v160 op_sel_hi:[0,0,0]
	v_mfma_scale_f32_16x16x128_f8f6f4 v[108:111], v[134:141], v[186:193], v[108:111], v160, v160 op_sel_hi:[0,0,0]
	v_mfma_scale_f32_16x16x128_f8f6f4 v[104:107], v[142:149], v[186:193], v[104:107], v160, v160 op_sel_hi:[0,0,0]
	v_mfma_scale_f32_16x16x128_f8f6f4 v[202:205], v[134:141], v[194:201], v[92:95], v160, v160 op_sel_hi:[0,0,0]
	v_mfma_scale_f32_16x16x128_f8f6f4 v[218:221], v[142:149], v[194:201], v[88:91], v160, v160 op_sel_hi:[0,0,0]
	v_mfma_scale_f32_16x16x128_f8f6f4 v[224:227], v[134:141], v[210:217], v[76:79], v160, v160 op_sel_hi:[0,0,0]
	v_mfma_scale_f32_16x16x128_f8f6f4 v[228:231], v[142:149], v[210:217], v[72:75], v160, v160 op_sel_hi:[0,0,0]
	s_setprio 0
	s_setprio 1
	v_mfma_scale_f32_16x16x128_f8f6f4 v[116:119], v[162:169], v[178:185], v[116:119], v160, v160 op_sel_hi:[0,0,0]
	v_mfma_scale_f32_16x16x128_f8f6f4 v[112:115], v[170:177], v[178:185], v[112:115], v160, v160 op_sel_hi:[0,0,0]
	v_mfma_scale_f32_16x16x128_f8f6f4 v[100:103], v[162:169], v[186:193], v[100:103], v160, v160 op_sel_hi:[0,0,0]
	v_mfma_scale_f32_16x16x128_f8f6f4 v[96:99], v[170:177], v[186:193], v[96:99], v160, v160 op_sel_hi:[0,0,0]
	v_mfma_scale_f32_16x16x128_f8f6f4 v[178:181], v[162:169], v[194:201], v[84:87], v160, v160 op_sel_hi:[0,0,0]
	v_mfma_scale_f32_16x16x128_f8f6f4 v[182:185], v[170:177], v[194:201], v[80:83], v160, v160 op_sel_hi:[0,0,0]
	v_mfma_scale_f32_16x16x128_f8f6f4 v[186:189], v[162:169], v[210:217], v[68:71], v160, v160 op_sel_hi:[0,0,0]
	v_mfma_scale_f32_16x16x128_f8f6f4 v[190:193], v[170:177], v[210:217], v[64:67], v160, v160 op_sel_hi:[0,0,0]
	s_setprio 0
	s_barrier
	v_mov_b32_e32 v128, v253
	s_add_i32 s89, s16, s18
	s_nop 2
	ds_read_b128 v[64:67], v159 offset:16384
	ds_read_b128 v[68:71], v159 offset:17408
	ds_read_b128 v[72:75], v159 offset:18432
	ds_read_b128 v[76:79], v159 offset:19456
	ds_read_b128 v[80:83], v159 offset:20480
	ds_read_b128 v[84:87], v159 offset:21504
	ds_read_b128 v[88:91], v159 offset:22528
	ds_read_b128 v[92:95], v159 offset:23552
	s_mov_b32 m0, s89
	s_nop 0
	global_load_lds_dwordx4 v128, s[10:11]
	v_mov_b32_e32 v128, v155
	s_add_i32 m0, s89, 0x2000
	s_add_u32 s94, s10, 0x80000
	global_load_lds_dwordx4 v128, s[10:11]
	s_addc_u32 s95, s11, 0
	v_mov_b32_e32 v128, v253
	s_add_i32 s89, s17, s18
	s_mov_b32 m0, s89
	s_nop 0
	global_load_lds_dwordx4 v128, s[94:95]
	v_mov_b32_e32 v128, v155
	s_add_i32 m0, s89, 0x2000
	s_nop 0
	global_load_lds_dwordx4 v128, s[94:95]
	v_mov_b32_e32 v128, v223
	s_mov_b32 m0, s3
	s_nop 0
	global_load_lds_dwordx4 v128, s[8:9]
	v_mov_b32_e32 v128, v154
	s_mov_b32 m0, s19
	s_nop 0
	global_load_lds_dwordx4 v128, s[8:9]
	s_waitcnt vmcnt(8)
	s_waitcnt lgkmcnt(0)
	s_barrier
	s_setprio 1
	v_mfma_scale_f32_16x16x128_f8f6f4 v[60:63], v[134:141], v[64:71], v[60:63], v160, v160 op_sel_hi:[0,0,0]
	v_mfma_scale_f32_16x16x128_f8f6f4 v[56:59], v[142:149], v[64:71], v[56:59], v160, v160 op_sel_hi:[0,0,0]
	v_mfma_scale_f32_16x16x128_f8f6f4 v[194:197], v[134:141], v[72:79], v[44:47], v160, v160 op_sel_hi:[0,0,0]
	v_mfma_scale_f32_16x16x128_f8f6f4 v[198:201], v[142:149], v[72:79], v[40:43], v160, v160 op_sel_hi:[0,0,0]
	v_mfma_scale_f32_16x16x128_f8f6f4 v[210:213], v[134:141], v[80:87], v[28:31], v160, v160 op_sel_hi:[0,0,0]
	v_mfma_scale_f32_16x16x128_f8f6f4 v[214:217], v[142:149], v[80:87], v[24:27], v160, v160 op_sel_hi:[0,0,0]
	v_mfma_scale_f32_16x16x128_f8f6f4 v[232:235], v[134:141], v[88:95], v[12:15], v160, v160 op_sel_hi:[0,0,0]
	v_mfma_scale_f32_16x16x128_f8f6f4 v[236:239], v[142:149], v[88:95], v[8:11], v160, v160 op_sel_hi:[0,0,0]
	s_setprio 0
	s_setprio 1
	v_mfma_scale_f32_16x16x128_f8f6f4 v[52:55], v[162:169], v[64:71], v[52:55], v160, v160 op_sel_hi:[0,0,0]
	v_mfma_scale_f32_16x16x128_f8f6f4 v[48:51], v[170:177], v[64:71], v[48:51], v160, v160 op_sel_hi:[0,0,0]
	v_mfma_scale_f32_16x16x128_f8f6f4 v[240:243], v[162:169], v[72:79], v[36:39], v160, v160 op_sel_hi:[0,0,0]
	v_mfma_scale_f32_16x16x128_f8f6f4 v[244:247], v[170:177], v[72:79], v[32:35], v160, v160 op_sel_hi:[0,0,0]
	v_mfma_scale_f32_16x16x128_f8f6f4 v[248:251], v[162:169], v[80:87], v[20:23], v160, v160 op_sel_hi:[0,0,0]
	v_mfma_scale_f32_16x16x128_f8f6f4 v[130:133], v[170:177], v[80:87], v[16:19], v160, v160 op_sel_hi:[0,0,0]
	v_mfma_scale_f32_16x16x128_f8f6f4 v[206:209], v[162:169], v[88:95], v[4:7], v160, v160 op_sel_hi:[0,0,0]
	v_mfma_scale_f32_16x16x128_f8f6f4 v[150:153], v[170:177], v[88:95], v[0:3], v160, v160 op_sel_hi:[0,0,0]
	s_setprio 0
	s_barrier
	s_add_i32 s89, 0, 0x18000
	v_add_u32_e32 v8, s89, v156
	s_add_i32 s96, 0, 0x1c000
	s_nop 1
	ds_read_b128 v[0:3], v8
	ds_read_b128 v[4:7], v8 offset:1024
	ds_read_b128 v[16:19], v8 offset:2048
	ds_read_b128 v[20:23], v8 offset:3072
	v_add_u32_e32 v8, s96, v156
	ds_read_b128 v[134:137], v8
	ds_read_b128 v[138:141], v8 offset:1024
	ds_read_b128 v[142:145], v8 offset:2048
	ds_read_b128 v[146:149], v8 offset:3072
	s_add_u32 s94, s8, 0x80000
	v_mov_b32_e32 v64, v223
	s_mov_b32 m0, s22
	ds_read_b128 v[8:11], v159 offset:32768
	ds_read_b128 v[12:15], v159 offset:33792
	ds_read_b128 v[24:27], v159 offset:34816
	ds_read_b128 v[28:31], v159 offset:35840
	ds_read_b128 v[32:35], v159 offset:36864
	ds_read_b128 v[36:39], v159 offset:37888
	ds_read_b128 v[40:43], v159 offset:38912
	ds_read_b128 v[44:47], v159 offset:39936
	s_addc_u32 s95, s9, 0
	s_nop 0
	global_load_lds_dwordx4 v64, s[94:95]
	v_mov_b32_e32 v64, v154
	s_mov_b32 m0, s24
	s_nop 0
	global_load_lds_dwordx4 v64, s[94:95]
	s_waitcnt vmcnt(8)
	s_waitcnt lgkmcnt(0)
	s_barrier
	s_setprio 1
	v_mfma_scale_f32_16x16x128_f8f6f4 v[124:127], v[0:7], v[8:15], v[124:127], v160, v160 op_sel_hi:[0,0,0]
	v_mfma_scale_f32_16x16x128_f8f6f4 v[120:123], v[16:23], v[8:15], v[120:123], v160, v160 op_sel_hi:[0,0,0]
	v_mfma_scale_f32_16x16x128_f8f6f4 v[108:111], v[0:7], v[24:31], v[108:111], v160, v160 op_sel_hi:[0,0,0]
	v_mfma_scale_f32_16x16x128_f8f6f4 v[104:107], v[16:23], v[24:31], v[104:107], v160, v160 op_sel_hi:[0,0,0]
	v_mfma_scale_f32_16x16x128_f8f6f4 v[92:95], v[0:7], v[32:39], v[202:205], v160, v160 op_sel_hi:[0,0,0]
	v_mfma_scale_f32_16x16x128_f8f6f4 v[88:91], v[16:23], v[32:39], v[218:221], v160, v160 op_sel_hi:[0,0,0]
	v_mfma_scale_f32_16x16x128_f8f6f4 v[76:79], v[0:7], v[40:47], v[224:227], v160, v160 op_sel_hi:[0,0,0]
	v_mfma_scale_f32_16x16x128_f8f6f4 v[72:75], v[16:23], v[40:47], v[228:231], v160, v160 op_sel_hi:[0,0,0]
	s_setprio 0
	s_setprio 1
	v_mfma_scale_f32_16x16x128_f8f6f4 v[116:119], v[134:141], v[8:15], v[116:119], v160, v160 op_sel_hi:[0,0,0]
	v_mfma_scale_f32_16x16x128_f8f6f4 v[112:115], v[142:149], v[8:15], v[112:115], v160, v160 op_sel_hi:[0,0,0]
	v_mfma_scale_f32_16x16x128_f8f6f4 v[100:103], v[134:141], v[24:31], v[100:103], v160, v160 op_sel_hi:[0,0,0]
	v_mfma_scale_f32_16x16x128_f8f6f4 v[96:99], v[142:149], v[24:31], v[96:99], v160, v160 op_sel_hi:[0,0,0]
	v_mfma_scale_f32_16x16x128_f8f6f4 v[84:87], v[134:141], v[32:39], v[178:181], v160, v160 op_sel_hi:[0,0,0]
	v_mfma_scale_f32_16x16x128_f8f6f4 v[80:83], v[142:149], v[32:39], v[182:185], v160, v160 op_sel_hi:[0,0,0]
	v_mfma_scale_f32_16x16x128_f8f6f4 v[68:71], v[134:141], v[40:47], v[186:189], v160, v160 op_sel_hi:[0,0,0]
	v_mfma_scale_f32_16x16x128_f8f6f4 v[64:67], v[142:149], v[40:47], v[190:193], v160, v160 op_sel_hi:[0,0,0]
	s_setprio 0
	s_barrier
	v_mov_b32_e32 v128, v253
	ds_read_b128 v[32:35], v159 offset:49152
	ds_read_b128 v[36:39], v159 offset:50176
	ds_read_b128 v[162:165], v159 offset:51200
	ds_read_b128 v[166:169], v159 offset:52224
	ds_read_b128 v[170:173], v159 offset:53248
	ds_read_b128 v[174:177], v159 offset:54272
	ds_read_b128 v[178:181], v159 offset:55296
	ds_read_b128 v[182:185], v159 offset:56320
	s_add_i32 s89, s89, s18
	v_lshl_add_u64 v[8:9], s[10:11], 0, v[128:129]
	v_lshl_add_u64 v[8:9], v[8:9], 0, s[26:27]
	s_mov_b32 m0, s89
	v_mov_b32_e32 v128, v155
	global_load_lds_dwordx4 v[8:9], off
	s_add_i32 m0, s89, 0x2000
	v_lshl_add_u64 v[8:9], s[10:11], 0, v[128:129]
	v_lshl_add_u64 v[8:9], v[8:9], 0, s[26:27]
	s_add_u32 s10, s10, 0x80080
	global_load_lds_dwordx4 v[8:9], off
	s_addc_u32 s11, s11, 0
	v_mov_b32_e32 v8, v253
	s_add_i32 s89, s96, s18
	s_mov_b32 m0, s89
	v_mov_b32_e32 v128, v223
	global_load_lds_dwordx4 v8, s[10:11]
	v_mov_b32_e32 v8, v155
	s_add_i32 m0, s89, 0x2000
	s_nop 0
	global_load_lds_dwordx4 v8, s[10:11]
	s_mov_b32 m0, s35
	v_lshl_add_u64 v[8:9], s[8:9], 0, v[128:129]
	v_lshl_add_u64 v[8:9], v[8:9], 0, s[26:27]
	v_mov_b32_e32 v128, v154
	global_load_lds_dwordx4 v[8:9], off
	s_mov_b32 m0, s44
	v_lshl_add_u64 v[8:9], s[8:9], 0, v[128:129]
	v_lshl_add_u64 v[8:9], v[8:9], 0, s[26:27]
	global_load_lds_dwordx4 v[8:9], off
	s_waitcnt vmcnt(8)
	s_waitcnt lgkmcnt(0)
	s_barrier
	s_setprio 1
	v_mfma_scale_f32_16x16x128_f8f6f4 v[60:63], v[0:7], v[32:39], v[60:63], v160, v160 op_sel_hi:[0,0,0]
	v_mfma_scale_f32_16x16x128_f8f6f4 v[56:59], v[16:23], v[32:39], v[56:59], v160, v160 op_sel_hi:[0,0,0]
	v_mfma_scale_f32_16x16x128_f8f6f4 v[44:47], v[0:7], v[162:169], v[194:197], v160, v160 op_sel_hi:[0,0,0]
	v_mfma_scale_f32_16x16x128_f8f6f4 v[40:43], v[16:23], v[162:169], v[198:201], v160, v160 op_sel_hi:[0,0,0]
	v_mfma_scale_f32_16x16x128_f8f6f4 v[28:31], v[0:7], v[170:177], v[210:213], v160, v160 op_sel_hi:[0,0,0]
	v_mfma_scale_f32_16x16x128_f8f6f4 v[24:27], v[16:23], v[170:177], v[214:217], v160, v160 op_sel_hi:[0,0,0]
	v_mfma_scale_f32_16x16x128_f8f6f4 v[12:15], v[0:7], v[178:185], v[232:235], v160, v160 op_sel_hi:[0,0,0]
	v_mfma_scale_f32_16x16x128_f8f6f4 v[8:11], v[16:23], v[178:185], v[236:239], v160, v160 op_sel_hi:[0,0,0]
	s_setprio 0
	s_setprio 1
	v_mfma_scale_f32_16x16x128_f8f6f4 v[52:55], v[134:141], v[32:39], v[52:55], v160, v160 op_sel_hi:[0,0,0]
	v_mfma_scale_f32_16x16x128_f8f6f4 v[48:51], v[142:149], v[32:39], v[48:51], v160, v160 op_sel_hi:[0,0,0]
	v_mfma_scale_f32_16x16x128_f8f6f4 v[36:39], v[134:141], v[162:169], v[240:243], v160, v160 op_sel_hi:[0,0,0]
	v_mfma_scale_f32_16x16x128_f8f6f4 v[32:35], v[142:149], v[162:169], v[244:247], v160, v160 op_sel_hi:[0,0,0]
	v_mfma_scale_f32_16x16x128_f8f6f4 v[20:23], v[134:141], v[170:177], v[248:251], v160, v160 op_sel_hi:[0,0,0]
	v_mfma_scale_f32_16x16x128_f8f6f4 v[16:19], v[142:149], v[170:177], v[130:133], v160, v160 op_sel_hi:[0,0,0]
	v_mfma_scale_f32_16x16x128_f8f6f4 v[4:7], v[134:141], v[178:185], v[206:209], v160, v160 op_sel_hi:[0,0,0]
	v_mfma_scale_f32_16x16x128_f8f6f4 v[0:3], v[142:149], v[178:185], v[150:153], v160, v160 op_sel_hi:[0,0,0]
	s_setprio 0
	s_barrier
	s_add_i32 s87, s87, 2
	s_add_u32 s6, s6, 0x100
	s_addc_u32 s7, s7, 0
	s_add_u32 s52, s52, 0x100
	s_addc_u32 s53, s53, 0
	s_cmp_gt_u32 s87, 29
	s_cbranch_scc0 .LBB0_183
	s_and_b64 vcc, exec, s[28:29]
	s_cbranch_vccz .LBB0_186
	s_barrier

.LBB0_601:
	ds_read_b128 v[128:131], v173
	ds_read_b128 v[132:135], v173 offset:1024
	ds_read_b128 v[154:157], v173 offset:2048
	ds_read_b128 v[158:161], v173 offset:3072
	ds_read_b128 v[162:165], v174
	ds_read_b128 v[166:169], v174 offset:1024
	ds_read_b128 v[176:179], v174 offset:2048
	ds_read_b128 v[180:183], v174 offset:3072
	s_add_u32 s8, s6, 0xfff00080
	s_addc_u32 s9, s7, -1
	s_cmp_eq_u32 s52, 60
	s_cselect_b32 s11, s5, s9
	s_cselect_b32 s10, s27, s8
	s_cselect_b32 s9, s38, s47
	s_cselect_b32 s8, s39, s46
	v_lshl_add_u64 v[170:171], s[6:7], 0, v[146:147]
	s_add_i32 m0, s77, 0xc000
	ds_read_b128 v[184:187], v175
	ds_read_b128 v[188:191], v175 offset:1024
	ds_read_b128 v[192:195], v175 offset:2048
	ds_read_b128 v[196:199], v175 offset:3072
	ds_read_b128 v[200:203], v175 offset:4096
	ds_read_b128 v[204:207], v175 offset:5120
	ds_read_b128 v[208:211], v175 offset:6144
	ds_read_b128 v[212:215], v175 offset:7168
	global_load_lds_dwordx4 v[170:171], off
	v_lshl_add_u64 v[170:171], s[6:7], 0, v[148:149]
	s_add_i32 m0, s77, 0xe000
	s_nop 0
	global_load_lds_dwordx4 v[170:171], off
	s_waitcnt vmcnt(8)
	s_waitcnt lgkmcnt(0)
	s_barrier
	s_setprio 1
	v_mfma_f32_16x16x32_f16 v[124:127], v[128:131], v[184:187], v[124:127]
	v_mfma_f32_16x16x32_f16 v[120:123], v[154:157], v[184:187], v[120:123]
	v_mfma_f32_16x16x32_f16 v[108:111], v[128:131], v[192:195], v[108:111]
	v_mfma_f32_16x16x32_f16 v[104:107], v[154:157], v[192:195], v[104:107]
	v_mfma_f32_16x16x32_f16 v[92:95], v[128:131], v[200:203], v[92:95]
	v_mfma_f32_16x16x32_f16 v[88:91], v[154:157], v[200:203], v[88:91]
	v_mfma_f32_16x16x32_f16 v[76:79], v[128:131], v[208:211], v[76:79]
	v_mfma_f32_16x16x32_f16 v[72:75], v[154:157], v[208:211], v[72:75]
	v_mfma_f32_16x16x32_f16 v[124:127], v[132:135], v[188:191], v[124:127]
	v_mfma_f32_16x16x32_f16 v[120:123], v[158:161], v[188:191], v[120:123]
	v_mfma_f32_16x16x32_f16 v[108:111], v[132:135], v[196:199], v[108:111]
	v_mfma_f32_16x16x32_f16 v[104:107], v[158:161], v[196:199], v[104:107]
	v_mfma_f32_16x16x32_f16 v[92:95], v[132:135], v[204:207], v[92:95]
	v_mfma_f32_16x16x32_f16 v[88:91], v[158:161], v[204:207], v[88:91]
	v_mfma_f32_16x16x32_f16 v[76:79], v[132:135], v[212:215], v[76:79]
	v_mfma_f32_16x16x32_f16 v[72:75], v[158:161], v[212:215], v[72:75]
	s_setprio 0
	s_setprio 1
	v_mfma_f32_16x16x32_f16 v[116:119], v[162:165], v[184:187], v[116:119]
	v_mfma_f32_16x16x32_f16 v[112:115], v[176:179], v[184:187], v[112:115]
	v_mfma_f32_16x16x32_f16 v[100:103], v[162:165], v[192:195], v[100:103]
	v_mfma_f32_16x16x32_f16 v[96:99], v[176:179], v[192:195], v[96:99]
	v_mfma_f32_16x16x32_f16 v[84:87], v[162:165], v[200:203], v[84:87]
	v_mfma_f32_16x16x32_f16 v[80:83], v[176:179], v[200:203], v[80:83]
	v_mfma_f32_16x16x32_f16 v[68:71], v[162:165], v[208:211], v[68:71]
	v_mfma_f32_16x16x32_f16 v[64:67], v[176:179], v[208:211], v[64:67]
	v_mfma_f32_16x16x32_f16 v[116:119], v[166:169], v[188:191], v[116:119]
	v_mfma_f32_16x16x32_f16 v[112:115], v[180:183], v[188:191], v[112:115]
	v_mfma_f32_16x16x32_f16 v[100:103], v[166:169], v[196:199], v[100:103]
	v_mfma_f32_16x16x32_f16 v[96:99], v[180:183], v[196:199], v[96:99]
	v_mfma_f32_16x16x32_f16 v[84:87], v[166:169], v[204:207], v[84:87]
	v_mfma_f32_16x16x32_f16 v[80:83], v[180:183], v[204:207], v[80:83]
	v_mfma_f32_16x16x32_f16 v[68:71], v[166:169], v[212:215], v[68:71]
	v_mfma_f32_16x16x32_f16 v[64:67], v[180:183], v[212:215], v[64:67]
	s_setprio 0
	s_barrier
	s_add_i32 s53, s45, s23
	v_lshl_add_u64 v[170:171], s[8:9], 0, v[138:139]
	s_mov_b32 m0, s53
	ds_read_b128 v[184:187], v175 offset:16384
	ds_read_b128 v[188:191], v175 offset:17408
	ds_read_b128 v[192:195], v175 offset:18432
	ds_read_b128 v[196:199], v175 offset:19456
	ds_read_b128 v[200:203], v175 offset:20480
	ds_read_b128 v[204:207], v175 offset:21504
	ds_read_b128 v[208:211], v175 offset:22528
	ds_read_b128 v[212:215], v175 offset:23552
	global_load_lds_dwordx4 v[170:171], off
	s_add_i32 m0, s53, 0x2000
	s_add_u32 s94, s8, 0x100000
	v_lshl_add_u64 v[216:217], s[8:9], 0, v[142:143]
	s_addc_u32 s95, s9, 0
	s_add_i32 s53, s34, s23
	global_load_lds_dwordx4 v[216:217], off
	v_lshl_add_u64 v[218:219], s[94:95], 0, v[138:139]
	s_mov_b32 m0, s53
	v_lshl_add_u64 v[220:221], s[10:11], 0, v[140:141]
	global_load_lds_dwordx4 v[218:219], off
	v_lshl_add_u64 v[218:219], s[94:95], 0, v[142:143]
	s_add_i32 m0, s53, 0x2000
	s_nop 0
	global_load_lds_dwordx4 v[218:219], off
	v_lshl_add_u64 v[218:219], s[10:11], 0, v[136:137]
	s_mov_b32 m0, s77
	s_nop 0
	global_load_lds_dwordx4 v[218:219], off
	s_mov_b32 m0, s85
	s_nop 0
	global_load_lds_dwordx4 v[220:221], off
	s_waitcnt vmcnt(8)
	s_waitcnt lgkmcnt(0)
	s_barrier
	s_setprio 1
	v_mfma_f32_16x16x32_f16 v[60:63], v[128:131], v[184:187], v[60:63]
	v_mfma_f32_16x16x32_f16 v[56:59], v[154:157], v[184:187], v[56:59]
	v_mfma_f32_16x16x32_f16 v[44:47], v[128:131], v[192:195], v[44:47]
	v_mfma_f32_16x16x32_f16 v[40:43], v[154:157], v[192:195], v[40:43]
	v_mfma_f32_16x16x32_f16 v[28:31], v[128:131], v[200:203], v[28:31]
	v_mfma_f32_16x16x32_f16 v[24:27], v[154:157], v[200:203], v[24:27]
	v_mfma_f32_16x16x32_f16 v[12:15], v[128:131], v[208:211], v[12:15]
	v_mfma_f32_16x16x32_f16 v[8:11], v[154:157], v[208:211], v[8:11]
	v_mfma_f32_16x16x32_f16 v[60:63], v[132:135], v[188:191], v[60:63]
	v_mfma_f32_16x16x32_f16 v[56:59], v[158:161], v[188:191], v[56:59]
	v_mfma_f32_16x16x32_f16 v[44:47], v[132:135], v[196:199], v[44:47]
	v_mfma_f32_16x16x32_f16 v[40:43], v[158:161], v[196:199], v[40:43]
	v_mfma_f32_16x16x32_f16 v[28:31], v[132:135], v[204:207], v[28:31]
	v_mfma_f32_16x16x32_f16 v[24:27], v[158:161], v[204:207], v[24:27]
	v_mfma_f32_16x16x32_f16 v[12:15], v[132:135], v[212:215], v[12:15]
	v_mfma_f32_16x16x32_f16 v[8:11], v[158:161], v[212:215], v[8:11]
	s_setprio 0
	s_setprio 1
	v_mfma_f32_16x16x32_f16 v[52:55], v[162:165], v[184:187], v[52:55]
	v_mfma_f32_16x16x32_f16 v[48:51], v[176:179], v[184:187], v[48:51]
	v_mfma_f32_16x16x32_f16 v[36:39], v[162:165], v[192:195], v[36:39]
	v_mfma_f32_16x16x32_f16 v[32:35], v[176:179], v[192:195], v[32:35]
	v_mfma_f32_16x16x32_f16 v[20:23], v[162:165], v[200:203], v[20:23]
	v_mfma_f32_16x16x32_f16 v[16:19], v[176:179], v[200:203], v[16:19]
	v_mfma_f32_16x16x32_f16 v[4:7], v[162:165], v[208:211], v[4:7]
	v_mfma_f32_16x16x32_f16 v[0:3], v[176:179], v[208:211], v[0:3]
	v_mfma_f32_16x16x32_f16 v[52:55], v[166:169], v[188:191], v[52:55]
	v_mfma_f32_16x16x32_f16 v[48:51], v[180:183], v[188:191], v[48:51]
	v_mfma_f32_16x16x32_f16 v[36:39], v[166:169], v[196:199], v[36:39]
	v_mfma_f32_16x16x32_f16 v[32:35], v[180:183], v[196:199], v[32:35]
	v_mfma_f32_16x16x32_f16 v[20:23], v[166:169], v[204:207], v[20:23]
	v_mfma_f32_16x16x32_f16 v[16:19], v[180:183], v[204:207], v[16:19]
	v_mfma_f32_16x16x32_f16 v[4:7], v[166:169], v[212:215], v[4:7]
	v_mfma_f32_16x16x32_f16 v[0:3], v[180:183], v[212:215], v[0:3]
	s_setprio 0
	s_barrier
	s_add_i32 s53, 0, 0x18000
	v_add_u32_e32 v144, s53, v172
	s_add_i32 s87, 0, 0x1c000
	ds_read_b128 v[128:131], v144
	ds_read_b128 v[132:135], v144 offset:1024
	ds_read_b128 v[154:157], v144 offset:2048
	ds_read_b128 v[158:161], v144 offset:3072
	v_add_u32_e32 v144, s87, v172
	ds_read_b128 v[162:165], v144
	ds_read_b128 v[166:169], v144 offset:1024
	ds_read_b128 v[176:179], v144 offset:2048
	ds_read_b128 v[180:183], v144 offset:3072
	s_add_u32 s10, s10, 0x100000
	s_addc_u32 s11, s11, 0
	s_mov_b32 m0, s66
	v_lshl_add_u64 v[224:225], s[10:11], 0, v[136:137]
	ds_read_b128 v[184:187], v175 offset:32768
	ds_read_b128 v[188:191], v175 offset:33792
	ds_read_b128 v[192:195], v175 offset:34816
	ds_read_b128 v[196:199], v175 offset:35840
	ds_read_b128 v[200:203], v175 offset:36864
	ds_read_b128 v[204:207], v175 offset:37888
	ds_read_b128 v[208:211], v175 offset:38912
	ds_read_b128 v[212:215], v175 offset:39936
	global_load_lds_dwordx4 v[224:225], off
	v_lshl_add_u64 v[224:225], s[10:11], 0, v[140:141]
	s_mov_b32 m0, s67
	s_nop 0
	global_load_lds_dwordx4 v[224:225], off
	s_waitcnt vmcnt(8)
	s_waitcnt lgkmcnt(0)
	s_barrier
	s_setprio 1
	v_mfma_f32_16x16x32_f16 v[124:127], v[128:131], v[184:187], v[124:127]
	v_mfma_f32_16x16x32_f16 v[120:123], v[154:157], v[184:187], v[120:123]
	v_mfma_f32_16x16x32_f16 v[108:111], v[128:131], v[192:195], v[108:111]
	v_mfma_f32_16x16x32_f16 v[104:107], v[154:157], v[192:195], v[104:107]
	v_mfma_f32_16x16x32_f16 v[92:95], v[128:131], v[200:203], v[92:95]
	v_mfma_f32_16x16x32_f16 v[88:91], v[154:157], v[200:203], v[88:91]
	v_mfma_f32_16x16x32_f16 v[76:79], v[128:131], v[208:211], v[76:79]
	v_mfma_f32_16x16x32_f16 v[72:75], v[154:157], v[208:211], v[72:75]
	v_mfma_f32_16x16x32_f16 v[124:127], v[132:135], v[188:191], v[124:127]
	v_mfma_f32_16x16x32_f16 v[120:123], v[158:161], v[188:191], v[120:123]
	v_mfma_f32_16x16x32_f16 v[108:111], v[132:135], v[196:199], v[108:111]
	v_mfma_f32_16x16x32_f16 v[104:107], v[158:161], v[196:199], v[104:107]
	v_mfma_f32_16x16x32_f16 v[92:95], v[132:135], v[204:207], v[92:95]
	v_mfma_f32_16x16x32_f16 v[88:91], v[158:161], v[204:207], v[88:91]
	v_mfma_f32_16x16x32_f16 v[76:79], v[132:135], v[212:215], v[76:79]
	v_mfma_f32_16x16x32_f16 v[72:75], v[158:161], v[212:215], v[72:75]
	s_setprio 0
	s_setprio 1
	v_mfma_f32_16x16x32_f16 v[116:119], v[162:165], v[184:187], v[116:119]
	v_mfma_f32_16x16x32_f16 v[112:115], v[176:179], v[184:187], v[112:115]
	v_mfma_f32_16x16x32_f16 v[100:103], v[162:165], v[192:195], v[100:103]
	v_mfma_f32_16x16x32_f16 v[96:99], v[176:179], v[192:195], v[96:99]
	v_mfma_f32_16x16x32_f16 v[84:87], v[162:165], v[200:203], v[84:87]
	v_mfma_f32_16x16x32_f16 v[80:83], v[176:179], v[200:203], v[80:83]
	v_mfma_f32_16x16x32_f16 v[68:71], v[162:165], v[208:211], v[68:71]
	v_mfma_f32_16x16x32_f16 v[64:67], v[176:179], v[208:211], v[64:67]
	v_mfma_f32_16x16x32_f16 v[116:119], v[166:169], v[188:191], v[116:119]
	v_mfma_f32_16x16x32_f16 v[112:115], v[180:183], v[188:191], v[112:115]
	v_mfma_f32_16x16x32_f16 v[100:103], v[166:169], v[196:199], v[100:103]
	v_mfma_f32_16x16x32_f16 v[96:99], v[180:183], v[196:199], v[96:99]
	v_mfma_f32_16x16x32_f16 v[84:87], v[166:169], v[204:207], v[84:87]
	v_mfma_f32_16x16x32_f16 v[80:83], v[180:183], v[204:207], v[80:83]
	v_mfma_f32_16x16x32_f16 v[68:71], v[166:169], v[212:215], v[68:71]
	v_mfma_f32_16x16x32_f16 v[64:67], v[180:183], v[212:215], v[64:67]
	s_setprio 0
	s_barrier
	s_add_i32 s10, s53, s23
	v_lshl_add_u64 v[170:171], v[170:171], 0, s[28:29]
	s_mov_b32 m0, s10
	ds_read_b128 v[184:187], v175 offset:49152
	ds_read_b128 v[188:191], v175 offset:50176
	ds_read_b128 v[192:195], v175 offset:51200
	ds_read_b128 v[196:199], v175 offset:52224
	ds_read_b128 v[200:203], v175 offset:53248
	ds_read_b128 v[204:207], v175 offset:54272
	ds_read_b128 v[208:211], v175 offset:55296
	ds_read_b128 v[212:215], v175 offset:56320
	global_load_lds_dwordx4 v[170:171], off
	s_add_i32 m0, s10, 0x2000
	s_add_u32 s8, s8, 0x100080
	v_lshl_add_u64 v[170:171], v[216:217], 0, s[28:29]
	s_addc_u32 s9, s9, 0
	s_add_i32 s10, s87, s23
	global_load_lds_dwordx4 v[170:171], off
	v_lshl_add_u64 v[170:171], s[8:9], 0, v[138:139]
	s_mov_b32 m0, s10
	s_nop 0
	global_load_lds_dwordx4 v[170:171], off
	v_lshl_add_u64 v[170:171], s[8:9], 0, v[142:143]
	s_add_i32 m0, s10, 0x2000
	s_nop 0
	global_load_lds_dwordx4 v[170:171], off
	v_lshl_add_u64 v[170:171], v[218:219], 0, s[28:29]
	s_mov_b32 m0, s18
	s_nop 0
	global_load_lds_dwordx4 v[170:171], off
	v_lshl_add_u64 v[170:171], v[220:221], 0, s[28:29]
	s_mov_b32 m0, s19
	s_nop 0
	global_load_lds_dwordx4 v[170:171], off
	s_waitcnt vmcnt(8)
	s_waitcnt lgkmcnt(0)
	s_barrier
	s_setprio 1
	v_mfma_f32_16x16x32_f16 v[60:63], v[128:131], v[184:187], v[60:63]
	v_mfma_f32_16x16x32_f16 v[56:59], v[154:157], v[184:187], v[56:59]
	v_mfma_f32_16x16x32_f16 v[44:47], v[128:131], v[192:195], v[44:47]
	v_mfma_f32_16x16x32_f16 v[40:43], v[154:157], v[192:195], v[40:43]
	v_mfma_f32_16x16x32_f16 v[28:31], v[128:131], v[200:203], v[28:31]
	v_mfma_f32_16x16x32_f16 v[24:27], v[154:157], v[200:203], v[24:27]
	v_mfma_f32_16x16x32_f16 v[12:15], v[128:131], v[208:211], v[12:15]
	v_mfma_f32_16x16x32_f16 v[8:11], v[154:157], v[208:211], v[8:11]
	v_mfma_f32_16x16x32_f16 v[60:63], v[132:135], v[188:191], v[60:63]
	v_mfma_f32_16x16x32_f16 v[56:59], v[158:161], v[188:191], v[56:59]
	v_mfma_f32_16x16x32_f16 v[44:47], v[132:135], v[196:199], v[44:47]
	v_mfma_f32_16x16x32_f16 v[40:43], v[158:161], v[196:199], v[40:43]
	v_mfma_f32_16x16x32_f16 v[28:31], v[132:135], v[204:207], v[28:31]
	v_mfma_f32_16x16x32_f16 v[24:27], v[158:161], v[204:207], v[24:27]
	v_mfma_f32_16x16x32_f16 v[12:15], v[132:135], v[212:215], v[12:15]
	v_mfma_f32_16x16x32_f16 v[8:11], v[158:161], v[212:215], v[8:11]
	s_setprio 0
	s_setprio 1
	v_mfma_f32_16x16x32_f16 v[52:55], v[162:165], v[184:187], v[52:55]
	v_mfma_f32_16x16x32_f16 v[48:51], v[176:179], v[184:187], v[48:51]
	v_mfma_f32_16x16x32_f16 v[36:39], v[162:165], v[192:195], v[36:39]
	v_mfma_f32_16x16x32_f16 v[32:35], v[176:179], v[192:195], v[32:35]
	v_mfma_f32_16x16x32_f16 v[20:23], v[162:165], v[200:203], v[20:23]
	v_mfma_f32_16x16x32_f16 v[16:19], v[176:179], v[200:203], v[16:19]
	v_mfma_f32_16x16x32_f16 v[4:7], v[162:165], v[208:211], v[4:7]
	v_mfma_f32_16x16x32_f16 v[0:3], v[176:179], v[208:211], v[0:3]
	v_mfma_f32_16x16x32_f16 v[52:55], v[166:169], v[188:191], v[52:55]
	v_mfma_f32_16x16x32_f16 v[48:51], v[180:183], v[188:191], v[48:51]
	v_mfma_f32_16x16x32_f16 v[36:39], v[166:169], v[196:199], v[36:39]
	v_mfma_f32_16x16x32_f16 v[32:35], v[180:183], v[196:199], v[32:35]
	v_mfma_f32_16x16x32_f16 v[20:23], v[166:169], v[204:207], v[20:23]
	v_mfma_f32_16x16x32_f16 v[16:19], v[180:183], v[204:207], v[16:19]
	v_mfma_f32_16x16x32_f16 v[4:7], v[166:169], v[212:215], v[4:7]
	v_mfma_f32_16x16x32_f16 v[0:3], v[180:183], v[212:215], v[0:3]
	s_setprio 0
	s_barrier
	s_add_i32 s52, s52, 2
	s_add_u32 s6, s6, 0x100
	s_addc_u32 s7, s7, 0
	s_add_u32 s46, s46, 0x100
	s_addc_u32 s47, s47, 0
	s_cmp_gt_u32 s52, 61
	s_cbranch_scc0 .LBB0_601
	s_and_b64 vcc, exec, s[30:31]
	s_cbranch_vccz .LBB0_604
	s_barrier

.LBB0_1741:
	v_add_u32_e32 v0, s59, v156
	ds_read_b128 v[132:135], v0
	ds_read_b128 v[136:139], v0 offset:1024
	ds_read_b128 v[140:143], v0 offset:2048
	ds_read_b128 v[144:147], v0 offset:3072
	v_add_u32_e32 v0, s60, v156
	s_add_u32 s72, s4, s30
	ds_read_b128 v[162:165], v0
	ds_read_b128 v[166:169], v0 offset:1024
	ds_read_b128 v[170:173], v0 offset:2048
	ds_read_b128 v[174:177], v0 offset:3072
	s_addc_u32 s73, s5, s31
	s_add_u32 s44, s72, 0x100
	s_addc_u32 s45, s73, 0
	s_add_u32 s46, s67, s30
	s_addc_u32 s47, s70, s31
	s_cmpk_eq_i32 s30, 0xf00
	s_cselect_b32 s45, s23, s45
	s_cselect_b32 s44, s63, s44
	s_cselect_b32 s47, s64, s47
	s_cselect_b32 s46, s65, s46
	v_mov_b32_e32 v0, v254
	ds_read_b128 v[178:181], v158
	ds_read_b128 v[182:185], v158 offset:1024
	ds_read_b128 v[186:189], v158 offset:2048
	ds_read_b128 v[190:193], v158 offset:3072
	ds_read_b128 v[194:197], v158 offset:4096
	ds_read_b128 v[198:201], v158 offset:5120
	ds_read_b128 v[210:213], v158 offset:6144
	ds_read_b128 v[214:217], v158 offset:7168
	s_add_i32 m0, s34, 0xc000
	v_lshl_add_u64 v[2:3], s[72:73], 0, v[0:1]
	v_lshl_add_u64 v[2:3], v[2:3], 0, s[12:13]
	v_mov_b32_e32 v0, v223
	global_load_lds_dwordx4 v[2:3], off
	s_add_i32 m0, s34, 0xe000
	v_lshl_add_u64 v[2:3], s[72:73], 0, v[0:1]
	v_lshl_add_u64 v[2:3], v[2:3], 0, s[12:13]
	global_load_lds_dwordx4 v[2:3], off
	s_waitcnt vmcnt(8)
	s_waitcnt lgkmcnt(0)
	s_barrier
	s_setprio 1
	v_mfma_scale_f32_16x16x128_f8f6f4 v[128:131], v[132:139], v[178:185], v[128:131], v159, v159 op_sel_hi:[0,0,0]
	v_mfma_scale_f32_16x16x128_f8f6f4 v[124:127], v[140:147], v[178:185], v[124:127], v159, v159 op_sel_hi:[0,0,0]
	v_mfma_scale_f32_16x16x128_f8f6f4 v[112:115], v[132:139], v[186:193], v[112:115], v159, v159 op_sel_hi:[0,0,0]
	v_mfma_scale_f32_16x16x128_f8f6f4 v[108:111], v[140:147], v[186:193], v[108:111], v159, v159 op_sel_hi:[0,0,0]
	v_mfma_scale_f32_16x16x128_f8f6f4 v[202:205], v[132:139], v[194:201], v[96:99], v159, v159 op_sel_hi:[0,0,0]
	v_mfma_scale_f32_16x16x128_f8f6f4 v[206:209], v[140:147], v[194:201], v[92:95], v159, v159 op_sel_hi:[0,0,0]
	v_mfma_scale_f32_16x16x128_f8f6f4 v[218:221], v[132:139], v[210:217], v[80:83], v159, v159 op_sel_hi:[0,0,0]
	v_mfma_scale_f32_16x16x128_f8f6f4 v[224:227], v[140:147], v[210:217], v[76:79], v159, v159 op_sel_hi:[0,0,0]
	s_setprio 0
	s_setprio 1
	v_mfma_scale_f32_16x16x128_f8f6f4 v[120:123], v[162:169], v[178:185], v[120:123], v159, v159 op_sel_hi:[0,0,0]
	v_mfma_scale_f32_16x16x128_f8f6f4 v[116:119], v[170:177], v[178:185], v[116:119], v159, v159 op_sel_hi:[0,0,0]
	v_mfma_scale_f32_16x16x128_f8f6f4 v[104:107], v[162:169], v[186:193], v[104:107], v159, v159 op_sel_hi:[0,0,0]
	v_mfma_scale_f32_16x16x128_f8f6f4 v[100:103], v[170:177], v[186:193], v[100:103], v159, v159 op_sel_hi:[0,0,0]
	v_mfma_scale_f32_16x16x128_f8f6f4 v[178:181], v[162:169], v[194:201], v[88:91], v159, v159 op_sel_hi:[0,0,0]
	v_mfma_scale_f32_16x16x128_f8f6f4 v[182:185], v[170:177], v[194:201], v[84:87], v159, v159 op_sel_hi:[0,0,0]
	v_mfma_scale_f32_16x16x128_f8f6f4 v[186:189], v[162:169], v[210:217], v[72:75], v159, v159 op_sel_hi:[0,0,0]
	v_mfma_scale_f32_16x16x128_f8f6f4 v[190:193], v[170:177], v[210:217], v[68:71], v159, v159 op_sel_hi:[0,0,0]
	s_setprio 0
	s_barrier
	v_mov_b32_e32 v0, v254
	s_add_i32 s72, s59, s33
	s_nop 2
	ds_read_b128 v[68:71], v158 offset:16384
	ds_read_b128 v[72:75], v158 offset:17408
	ds_read_b128 v[76:79], v158 offset:18432
	ds_read_b128 v[80:83], v158 offset:19456
	ds_read_b128 v[84:87], v158 offset:20480
	ds_read_b128 v[88:91], v158 offset:21504
	ds_read_b128 v[92:95], v158 offset:22528
	ds_read_b128 v[96:99], v158 offset:23552
	s_mov_b32 m0, s72
	s_nop 0
	global_load_lds_dwordx4 v0, s[46:47]
	v_mov_b32_e32 v0, v223
	s_add_i32 m0, s72, 0x2000
	s_add_u32 s72, s46, 0x80000
	global_load_lds_dwordx4 v0, s[46:47]
	s_addc_u32 s73, s47, 0
	v_mov_b32_e32 v0, v254
	s_add_i32 s75, s60, s33
	s_mov_b32 m0, s75
	s_nop 0
	global_load_lds_dwordx4 v0, s[72:73]
	v_mov_b32_e32 v0, v223
	s_add_i32 m0, s75, 0x2000
	s_nop 0
	global_load_lds_dwordx4 v0, s[72:73]
	v_mov_b32_e32 v0, v254
	s_mov_b32 m0, s34
	s_nop 0
	global_load_lds_dwordx4 v0, s[44:45]
	v_mov_b32_e32 v0, v223
	s_mov_b32 m0, s35
	s_nop 0
	global_load_lds_dwordx4 v0, s[44:45]
	s_waitcnt vmcnt(8)
	s_waitcnt lgkmcnt(0)
	s_barrier
	s_setprio 1
	v_mfma_scale_f32_16x16x128_f8f6f4 v[64:67], v[132:139], v[68:75], v[64:67], v159, v159 op_sel_hi:[0,0,0]
	v_mfma_scale_f32_16x16x128_f8f6f4 v[60:63], v[140:147], v[68:75], v[60:63], v159, v159 op_sel_hi:[0,0,0]
	v_mfma_scale_f32_16x16x128_f8f6f4 v[194:197], v[132:139], v[76:83], v[48:51], v159, v159 op_sel_hi:[0,0,0]
	v_mfma_scale_f32_16x16x128_f8f6f4 v[198:201], v[140:147], v[76:83], v[44:47], v159, v159 op_sel_hi:[0,0,0]
	v_mfma_scale_f32_16x16x128_f8f6f4 v[210:213], v[132:139], v[84:91], v[32:35], v159, v159 op_sel_hi:[0,0,0]
	v_mfma_scale_f32_16x16x128_f8f6f4 v[214:217], v[140:147], v[84:91], v[28:31], v159, v159 op_sel_hi:[0,0,0]
	v_mfma_scale_f32_16x16x128_f8f6f4 v[228:231], v[132:139], v[92:99], v[16:19], v159, v159 op_sel_hi:[0,0,0]
	v_mfma_scale_f32_16x16x128_f8f6f4 v[232:235], v[140:147], v[92:99], v[12:15], v159, v159 op_sel_hi:[0,0,0]
	s_setprio 0
	s_setprio 1
	v_mfma_scale_f32_16x16x128_f8f6f4 v[56:59], v[162:169], v[68:75], v[56:59], v159, v159 op_sel_hi:[0,0,0]
	v_mfma_scale_f32_16x16x128_f8f6f4 v[52:55], v[170:177], v[68:75], v[52:55], v159, v159 op_sel_hi:[0,0,0]
	v_mfma_scale_f32_16x16x128_f8f6f4 v[236:239], v[162:169], v[76:83], v[40:43], v159, v159 op_sel_hi:[0,0,0]
	v_mfma_scale_f32_16x16x128_f8f6f4 v[240:243], v[170:177], v[76:83], v[36:39], v159, v159 op_sel_hi:[0,0,0]
	v_mfma_scale_f32_16x16x128_f8f6f4 v[244:247], v[162:169], v[84:91], v[24:27], v159, v159 op_sel_hi:[0,0,0]
	v_mfma_scale_f32_16x16x128_f8f6f4 v[248:251], v[170:177], v[84:91], v[20:23], v159, v159 op_sel_hi:[0,0,0]
	v_mfma_scale_f32_16x16x128_f8f6f4 v[148:151], v[162:169], v[92:99], v[8:11], v159, v159 op_sel_hi:[0,0,0]
	v_mfma_scale_f32_16x16x128_f8f6f4 v[152:155], v[170:177], v[92:99], v[4:7], v159, v159 op_sel_hi:[0,0,0]
	s_setprio 0
	s_barrier
	s_add_i32 s75, 0, 0x18000
	v_add_u32_e32 v0, s75, v156
	s_add_i32 s76, 0, 0x1c000
	s_nop 1
	ds_read_b128 v[2:5], v0
	ds_read_b128 v[6:9], v0 offset:1024
	ds_read_b128 v[20:23], v0 offset:2048
	ds_read_b128 v[24:27], v0 offset:3072
	v_add_u32_e32 v0, s76, v156
	ds_read_b128 v[132:135], v0
	ds_read_b128 v[136:139], v0 offset:1024
	ds_read_b128 v[140:143], v0 offset:2048
	ds_read_b128 v[144:147], v0 offset:3072
	s_add_u32 s72, s44, 0x80000
	v_mov_b32_e32 v0, v254
	s_mov_b32 m0, s38
	ds_read_b128 v[10:13], v158 offset:32768
	ds_read_b128 v[14:17], v158 offset:33792
	ds_read_b128 v[28:31], v158 offset:34816
	ds_read_b128 v[32:35], v158 offset:35840
	ds_read_b128 v[36:39], v158 offset:36864
	ds_read_b128 v[40:43], v158 offset:37888
	ds_read_b128 v[44:47], v158 offset:38912
	ds_read_b128 v[48:51], v158 offset:39936
	s_addc_u32 s73, s45, 0
	s_nop 0
	global_load_lds_dwordx4 v0, s[72:73]
	v_mov_b32_e32 v0, v223
	s_mov_b32 m0, s39
	s_nop 0
	global_load_lds_dwordx4 v0, s[72:73]
	s_waitcnt vmcnt(8)
	s_waitcnt lgkmcnt(0)
	s_barrier
	s_setprio 1
	v_mfma_scale_f32_16x16x128_f8f6f4 v[128:131], v[2:9], v[10:17], v[128:131], v159, v159 op_sel_hi:[0,0,0]
	v_mfma_scale_f32_16x16x128_f8f6f4 v[124:127], v[20:27], v[10:17], v[124:127], v159, v159 op_sel_hi:[0,0,0]
	v_mfma_scale_f32_16x16x128_f8f6f4 v[112:115], v[2:9], v[28:35], v[112:115], v159, v159 op_sel_hi:[0,0,0]
	v_mfma_scale_f32_16x16x128_f8f6f4 v[108:111], v[20:27], v[28:35], v[108:111], v159, v159 op_sel_hi:[0,0,0]
	v_mfma_scale_f32_16x16x128_f8f6f4 v[96:99], v[2:9], v[36:43], v[202:205], v159, v159 op_sel_hi:[0,0,0]
	v_mfma_scale_f32_16x16x128_f8f6f4 v[92:95], v[20:27], v[36:43], v[206:209], v159, v159 op_sel_hi:[0,0,0]
	v_mfma_scale_f32_16x16x128_f8f6f4 v[80:83], v[2:9], v[44:51], v[218:221], v159, v159 op_sel_hi:[0,0,0]
	v_mfma_scale_f32_16x16x128_f8f6f4 v[76:79], v[20:27], v[44:51], v[224:227], v159, v159 op_sel_hi:[0,0,0]
	s_setprio 0
	s_setprio 1
	v_mfma_scale_f32_16x16x128_f8f6f4 v[120:123], v[132:139], v[10:17], v[120:123], v159, v159 op_sel_hi:[0,0,0]
	v_mfma_scale_f32_16x16x128_f8f6f4 v[116:119], v[140:147], v[10:17], v[116:119], v159, v159 op_sel_hi:[0,0,0]
	v_mfma_scale_f32_16x16x128_f8f6f4 v[104:107], v[132:139], v[28:35], v[104:107], v159, v159 op_sel_hi:[0,0,0]
	v_mfma_scale_f32_16x16x128_f8f6f4 v[100:103], v[140:147], v[28:35], v[100:103], v159, v159 op_sel_hi:[0,0,0]
	v_mfma_scale_f32_16x16x128_f8f6f4 v[88:91], v[132:139], v[36:43], v[178:181], v159, v159 op_sel_hi:[0,0,0]
	v_mfma_scale_f32_16x16x128_f8f6f4 v[84:87], v[140:147], v[36:43], v[182:185], v159, v159 op_sel_hi:[0,0,0]
	v_mfma_scale_f32_16x16x128_f8f6f4 v[72:75], v[132:139], v[44:51], v[186:189], v159, v159 op_sel_hi:[0,0,0]
	v_mfma_scale_f32_16x16x128_f8f6f4 v[68:71], v[140:147], v[44:51], v[190:193], v159, v159 op_sel_hi:[0,0,0]
	s_setprio 0
	s_barrier
	v_mov_b32_e32 v0, v254
	ds_read_b128 v[36:39], v158 offset:49152
	ds_read_b128 v[40:43], v158 offset:50176
	ds_read_b128 v[162:165], v158 offset:51200
	ds_read_b128 v[166:169], v158 offset:52224
	ds_read_b128 v[170:173], v158 offset:53248
	ds_read_b128 v[174:177], v158 offset:54272
	ds_read_b128 v[178:181], v158 offset:55296
	ds_read_b128 v[182:185], v158 offset:56320
	s_add_i32 s72, s75, s33
	v_lshl_add_u64 v[10:11], s[46:47], 0, v[0:1]
	v_lshl_add_u64 v[10:11], v[10:11], 0, s[10:11]
	s_mov_b32 m0, s72
	v_mov_b32_e32 v0, v223
	global_load_lds_dwordx4 v[10:11], off
	s_add_i32 m0, s72, 0x2000
	s_nop 0
	v_lshl_add_u64 v[10:11], s[46:47], 0, v[0:1]
	s_add_u32 s46, s46, 0x80080
	v_lshl_add_u64 v[10:11], v[10:11], 0, s[10:11]
	s_addc_u32 s47, s47, 0
	v_mov_b32_e32 v0, v254
	s_add_i32 s72, s76, s33
	global_load_lds_dwordx4 v[10:11], off
	s_mov_b32 m0, s72
	s_nop 0
	global_load_lds_dwordx4 v0, s[46:47]
	v_mov_b32_e32 v0, v223
	s_add_i32 m0, s72, 0x2000
	s_nop 0
	global_load_lds_dwordx4 v0, s[46:47]
	v_mov_b32_e32 v0, v254
	s_mov_b32 m0, s50
	v_lshl_add_u64 v[10:11], s[44:45], 0, v[0:1]
	v_lshl_add_u64 v[10:11], v[10:11], 0, s[10:11]
	v_mov_b32_e32 v0, v223
	global_load_lds_dwordx4 v[10:11], off
	s_mov_b32 m0, s51
	v_lshl_add_u64 v[10:11], s[44:45], 0, v[0:1]
	v_lshl_add_u64 v[10:11], v[10:11], 0, s[10:11]
	global_load_lds_dwordx4 v[10:11], off
	s_waitcnt vmcnt(8)
	s_waitcnt lgkmcnt(0)
	s_barrier
	s_setprio 1
	v_mfma_scale_f32_16x16x128_f8f6f4 v[64:67], v[2:9], v[36:43], v[64:67], v159, v159 op_sel_hi:[0,0,0]
	v_mfma_scale_f32_16x16x128_f8f6f4 v[60:63], v[20:27], v[36:43], v[60:63], v159, v159 op_sel_hi:[0,0,0]
	v_mfma_scale_f32_16x16x128_f8f6f4 v[48:51], v[2:9], v[162:169], v[194:197], v159, v159 op_sel_hi:[0,0,0]
	v_mfma_scale_f32_16x16x128_f8f6f4 v[44:47], v[20:27], v[162:169], v[198:201], v159, v159 op_sel_hi:[0,0,0]
	v_mfma_scale_f32_16x16x128_f8f6f4 v[32:35], v[2:9], v[170:177], v[210:213], v159, v159 op_sel_hi:[0,0,0]
	v_mfma_scale_f32_16x16x128_f8f6f4 v[28:31], v[20:27], v[170:177], v[214:217], v159, v159 op_sel_hi:[0,0,0]
	v_mfma_scale_f32_16x16x128_f8f6f4 v[16:19], v[2:9], v[178:185], v[228:231], v159, v159 op_sel_hi:[0,0,0]
	v_mfma_scale_f32_16x16x128_f8f6f4 v[12:15], v[20:27], v[178:185], v[232:235], v159, v159 op_sel_hi:[0,0,0]
	s_setprio 0
	s_setprio 1
	v_mfma_scale_f32_16x16x128_f8f6f4 v[56:59], v[132:139], v[36:43], v[56:59], v159, v159 op_sel_hi:[0,0,0]
	v_mfma_scale_f32_16x16x128_f8f6f4 v[52:55], v[140:147], v[36:43], v[52:55], v159, v159 op_sel_hi:[0,0,0]
	v_mfma_scale_f32_16x16x128_f8f6f4 v[40:43], v[132:139], v[162:169], v[236:239], v159, v159 op_sel_hi:[0,0,0]
	v_mfma_scale_f32_16x16x128_f8f6f4 v[36:39], v[140:147], v[162:169], v[240:243], v159, v159 op_sel_hi:[0,0,0]
	v_mfma_scale_f32_16x16x128_f8f6f4 v[24:27], v[132:139], v[170:177], v[244:247], v159, v159 op_sel_hi:[0,0,0]
	v_mfma_scale_f32_16x16x128_f8f6f4 v[20:23], v[140:147], v[170:177], v[248:251], v159, v159 op_sel_hi:[0,0,0]
	v_mfma_scale_f32_16x16x128_f8f6f4 v[8:11], v[132:139], v[178:185], v[148:151], v159, v159 op_sel_hi:[0,0,0]
	v_mfma_scale_f32_16x16x128_f8f6f4 v[4:7], v[140:147], v[178:185], v[152:155], v159, v159 op_sel_hi:[0,0,0]
	s_setprio 0
	s_barrier
	s_add_i32 s71, s71, 2
	s_add_u32 s30, s30, 0x100
	s_addc_u32 s31, s31, 0
	s_cmp_gt_u32 s71, 29
	s_cbranch_scc1 .LBB0_1744
